# nt hint on the read-once f32 weight loads of the P0 transposes (tr_all)
# baseline (speedup 1.0000x reference)
; __device__ __forceinline__ TrJob tr_job(const Params& p, int j) {
;     ...
;     else if (j < 6144) { const int jj = j - 5120, nc = jj >> 5, kc = jj & 31;
;         t.src = (kc < 16 ? p.wpp + (size_t)(kc * 64) * D : p.wpc + (size_t)((kc - 16) * 64) * D) + nc * 64; t.sld = D; t.dst = (bf16_t*)(p.ws + WS_BP) + (size_t)(nc * 64) * LDP + kc * 64; }
;     else { const int jj = j - 6144, nc = jj >> 5, kc = jj & 31; t.src = p.wout + (size_t)(kc * 64) * D + nc * 64; t.sld = D; t.dst = (bf16_t*)(p.ws + WS_BO) + (size_t)(nc * 64) * LDP + kc * 64; }
; __device__ __forceinline__ void tr_load4(const Params& p, int j0, int tid, f32x4 (&v)[4][2]) {
; #pragma unroll
;     for (int q = 0; q < 4; ++q) { const TrJob t = tr_job(p, j0 + q);
; #pragma unroll
;         for (int i = 0; i < 2; ++i) { const int idx = tid + i * 512, kr = idx >> 4, c4 = idx & 15; v[q][i] = *(const f32x4*)(t.src + (size_t)kr * t.sld + c4 * 4); } }
.LBB0_166:
	v_lshlrev_b32_e32 v2, 2, v35
	v_and_b32_e32 v2, 60, v2
	v_mov_b32_e32 v27, 0
	v_ashrrev_i32_e32 v28, 4, v35
	v_lshlrev_b32_e32 v26, 2, v2
	v_lshl_add_u64 v[2:3], s[2:3], 0, v[26:27]
	v_mad_i64_i32 v[4:5], s[0:1], s40, v28, 0
	v_lshl_add_u64 v[10:11], v[4:5], 2, v[2:3]
	v_add_u32_e32 v4, 0x200, v35
	v_ashrrev_i32_e32 v29, 4, v4
	v_mad_i64_i32 v[4:5], s[0:1], s40, v29, 0
	v_lshl_add_u64 v[12:13], v[4:5], 2, v[2:3]
	global_load_dwordx4 v[2:5], v[10:11], off nt
	global_load_dwordx4 v[6:9], v[12:13], off nt
	v_cndmask_b32_e64 v10, 0, 1, s[6:7]
	v_cmp_ne_u32_e64 s[2:3], 1, v10
	s_andn2_b64 vcc, exec, s[6:7]
	s_or_b32 s0, s31, 1
	s_cbranch_vccnz .LBB0_169
	s_cmpk_lt_u32 s31, 0x1800
	s_cbranch_scc1 .LBB0_170
	s_lshl_b32 s1, s0, 19
	s_and_b32 s1, s1, 0xe80000
	s_add_u32 s1, s20, s1
	s_mov_b32 s7, 0
	s_addc_u32 s9, s21, 0
	s_and_b32 s6, s30, 0x7fffffc0
	s_lshl_b64 s[6:7], s[6:7], 2
	s_add_u32 s1, s1, s6
	s_addc_u32 s7, s9, s7
	s_add_u32 s6, s1, 0xffff4000
	s_addc_u32 s7, s7, -1
	s_cbranch_execz .LBB0_171
	s_branch .LBB0_176

; __device__ __forceinline__ TrJob tr_job(const Params& p, int j) {
;     ...
;     else if (j < 6144) { const int jj = j - 5120, nc = jj >> 5, kc = jj & 31;
;         t.src = (kc < 16 ? p.wpp + (size_t)(kc * 64) * D : p.wpc + (size_t)((kc - 16) * 64) * D) + nc * 64; t.sld = D; t.dst = (bf16_t*)(p.ws + WS_BP) + (size_t)(nc * 64) * LDP + kc * 64; }
;     else { const int jj = j - 6144, nc = jj >> 5, kc = jj & 31; t.src = p.wout + (size_t)(kc * 64) * D + nc * 64; t.sld = D; t.dst = (bf16_t*)(p.ws + WS_BO) + (size_t)(nc * 64) * LDP + kc * 64; }
; __device__ __forceinline__ void tr_load4(const Params& p, int j0, int tid, f32x4 (&v)[4][2]) {
; #pragma unroll
;     for (int q = 0; q < 4; ++q) { const TrJob t = tr_job(p, j0 + q);
; #pragma unroll
;         for (int i = 0; i < 2; ++i) { const int idx = tid + i * 512, kr = idx >> 4, c4 = idx & 15; v[q][i] = *(const f32x4*)(t.src + (size_t)kr * t.sld + c4 * 4); } }
.LBB0_196:
	v_mov_b32_e32 v27, 0
	v_lshl_add_u64 v[10:11], s[6:7], 0, v[26:27]
	v_mad_i64_i32 v[12:13], s[0:1], s40, v28, 0
	v_lshl_add_u64 v[18:19], v[12:13], 2, v[10:11]
	v_mad_i64_i32 v[12:13], s[0:1], s40, v29, 0
	v_lshl_add_u64 v[20:21], v[12:13], 2, v[10:11]
	global_load_dwordx4 v[10:13], v[18:19], off nt
	global_load_dwordx4 v[14:17], v[20:21], off nt
	s_and_b64 vcc, exec, s[2:3]
	s_or_b32 s0, s31, 2
	s_cbranch_vccnz .LBB0_199
	s_cmpk_lt_u32 s31, 0x1800
	s_cbranch_scc1 .LBB0_200
	s_lshl_b32 s1, s0, 19
	s_and_b32 s1, s1, 0xf00000
	s_add_u32 s1, s20, s1
	s_mov_b32 s7, 0
	s_addc_u32 s9, s21, 0
	s_and_b32 s6, s30, 0x7fffffc0
	s_lshl_b64 s[6:7], s[6:7], 2
	s_add_u32 s1, s1, s6
	s_addc_u32 s7, s9, s7
	s_add_u32 s6, s1, 0xffff4000
	s_addc_u32 s7, s7, -1
	s_cbranch_execz .LBB0_201
	s_branch .LBB0_206

; __device__ __forceinline__ TrJob tr_job(const Params& p, int j) {
;     ...
;     else if (j < 6144) { const int jj = j - 5120, nc = jj >> 5, kc = jj & 31;
;         t.src = (kc < 16 ? p.wpp + (size_t)(kc * 64) * D : p.wpc + (size_t)((kc - 16) * 64) * D) + nc * 64; t.sld = D; t.dst = (bf16_t*)(p.ws + WS_BP) + (size_t)(nc * 64) * LDP + kc * 64; }
;     else { const int jj = j - 6144, nc = jj >> 5, kc = jj & 31; t.src = p.wout + (size_t)(kc * 64) * D + nc * 64; t.sld = D; t.dst = (bf16_t*)(p.ws + WS_BO) + (size_t)(nc * 64) * LDP + kc * 64; }
; __device__ __forceinline__ void tr_load4(const Params& p, int j0, int tid, f32x4 (&v)[4][2]) {
; #pragma unroll
;     for (int q = 0; q < 4; ++q) { const TrJob t = tr_job(p, j0 + q);
; #pragma unroll
;         for (int i = 0; i < 2; ++i) { const int idx = tid + i * 512, kr = idx >> 4, c4 = idx & 15; v[q][i] = *(const f32x4*)(t.src + (size_t)kr * t.sld + c4 * 4); } }
.LBB0_226:
	v_mov_b32_e32 v27, 0
	v_lshl_add_u64 v[18:19], s[6:7], 0, v[26:27]
	v_mad_i64_i32 v[20:21], s[0:1], s40, v28, 0
	v_lshl_add_u64 v[30:31], v[20:21], 2, v[18:19]
	v_mad_i64_i32 v[20:21], s[0:1], s40, v29, 0
	v_lshl_add_u64 v[32:33], v[20:21], 2, v[18:19]
	global_load_dwordx4 v[18:21], v[30:31], off nt
	global_load_dwordx4 v[22:25], v[32:33], off nt
	s_and_b64 vcc, exec, s[2:3]
	s_or_b32 s0, s31, 3
	s_cbranch_vccnz .LBB0_229
	s_cmpk_lt_u32 s31, 0x1800
	s_cbranch_scc1 .LBB0_230
	s_lshl_b32 s1, s0, 19
	s_and_b32 s1, s1, 0xf80000
	s_add_u32 s1, s20, s1
	s_mov_b32 s3, 0
	s_addc_u32 s6, s21, 0
	s_and_b32 s2, s30, 0x7fffffc0
	s_lshl_b64 s[2:3], s[2:3], 2
	s_add_u32 s1, s1, s2
	s_addc_u32 s3, s6, s3
	s_add_u32 s2, s1, 0xffff4000
	s_addc_u32 s3, s3, -1
	s_cbranch_execz .LBB0_231
	s_branch .LBB0_236

; __device__ __forceinline__ void tr_load4(const Params& p, int j0, int tid, f32x4 (&v)[4][2]) {
; #pragma unroll
;     for (int q = 0; q < 4; ++q) { const TrJob t = tr_job(p, j0 + q);
; #pragma unroll
;         for (int i = 0; i < 2; ++i) { const int idx = tid + i * 512, kr = idx >> 4, c4 = idx & 15; v[q][i] = *(const f32x4*)(t.src + (size_t)kr * t.sld + c4 * 4); } }
.LBB0_256:
	v_mov_b32_e32 v27, 0
	v_lshl_add_u64 v[26:27], s[2:3], 0, v[26:27]
	v_mad_i64_i32 v[30:31], s[0:1], s6, v28, 0
	v_lshl_add_u64 v[36:37], v[30:31], 2, v[26:27]
	v_mad_i64_i32 v[28:29], s[0:1], s6, v29, 0
	v_lshl_add_u64 v[38:39], v[28:29], 2, v[26:27]
	global_load_dwordx4 v[26:29], v[36:37], off nt
	global_load_dwordx4 v[30:33], v[38:39], off nt

; __device__ __forceinline__ TrJob tr_job(const Params& p, int j) {
;     ...
;     else if (j < 6144) { const int jj = j - 5120, nc = jj >> 5, kc = jj & 31;
;         t.src = (kc < 16 ? p.wpp + (size_t)(kc * 64) * D : p.wpc + (size_t)((kc - 16) * 64) * D) + nc * 64; t.sld = D; t.dst = (bf16_t*)(p.ws + WS_BP) + (size_t)(nc * 64) * LDP + kc * 64; }
;     else { const int jj = j - 6144, nc = jj >> 5, kc = jj & 31; t.src = p.wout + (size_t)(kc * 64) * D + nc * 64; t.sld = D; t.dst = (bf16_t*)(p.ws + WS_BO) + (size_t)(nc * 64) * LDP + kc * 64; }
; __device__ __forceinline__ void tr_load4(const Params& p, int j0, int tid, f32x4 (&v)[4][2]) {
; #pragma unroll
;     for (int q = 0; q < 4; ++q) { const TrJob t = tr_job(p, j0 + q);
; #pragma unroll
;         for (int i = 0; i < 2; ++i) { const int idx = tid + i * 512, kr = idx >> 4, c4 = idx & 15; v[q][i] = *(const f32x4*)(t.src + (size_t)kr * t.sld + c4 * 4); } }
; __device__ __forceinline__ void tr_all(const Params& p, LAS float* sm, int b, int G, int tid) {
;     ...
;         if (nb < 1792) tr_load4(p, nb * 4, tid, v);
.LBB0_289:
	v_lshlrev_b32_e32 v38, 2, v36
	v_lshl_add_u64 v[2:3], s[4:5], 0, v[38:39]
	v_mad_i64_i32 v[4:5], s[0:1], s52, v40, 0
	v_mad_i64_i32 v[6:7], s[0:1], s52, v42, 0
	v_lshl_add_u64 v[4:5], v[4:5], 2, v[2:3]
	v_lshl_add_u64 v[6:7], v[6:7], 2, v[2:3]
	global_load_dwordx4 v[2:5], v[4:5], off nt
	s_nop 0
	global_load_dwordx4 v[6:9], v[6:7], off nt
	v_cndmask_b32_e64 v10, 0, 1, s[50:51]
	s_or_b32 s0, s55, 1
	v_cmp_ne_u32_e64 s[4:5], 1, v10
	s_andn2_b64 vcc, exec, s[50:51]
	s_mov_b64 s[52:53], -1
	s_cbranch_vccnz .LBB0_299
	s_cmpk_lt_u32 s55, 0x1800
	s_cbranch_scc1 .LBB0_292
	s_lshl_b32 s1, s0, 19
	s_and_b32 s1, s1, 0xe80000
	s_add_u32 s1, s20, s1
	s_addc_u32 s9, s21, 0
	s_lshl_b32 s6, s89, 3
	s_and_b32 s6, s6, 0x7fffffc0
	s_lshl_b64 s[28:29], s[6:7], 2
	s_add_u32 s1, s1, s28
	s_addc_u32 s6, s9, s29
	s_add_u32 s50, s1, 0xffff4000
	s_addc_u32 s51, s6, -1
	s_mov_b64 s[52:53], 0

; __device__ __forceinline__ TrJob tr_job(const Params& p, int j) {
;     ...
;     else if (j < 6144) { const int jj = j - 5120, nc = jj >> 5, kc = jj & 31;
;         t.src = (kc < 16 ? p.wpp + (size_t)(kc * 64) * D : p.wpc + (size_t)((kc - 16) * 64) * D) + nc * 64; t.sld = D; t.dst = (bf16_t*)(p.ws + WS_BP) + (size_t)(nc * 64) * LDP + kc * 64; }
;     else { const int jj = j - 6144, nc = jj >> 5, kc = jj & 31; t.src = p.wout + (size_t)(kc * 64) * D + nc * 64; t.sld = D; t.dst = (bf16_t*)(p.ws + WS_BO) + (size_t)(nc * 64) * LDP + kc * 64; }
; __device__ __forceinline__ void tr_load4(const Params& p, int j0, int tid, f32x4 (&v)[4][2]) {
; #pragma unroll
;     for (int q = 0; q < 4; ++q) { const TrJob t = tr_job(p, j0 + q);
; #pragma unroll
;         for (int i = 0; i < 2; ++i) { const int idx = tid + i * 512, kr = idx >> 4, c4 = idx & 15; v[q][i] = *(const f32x4*)(t.src + (size_t)kr * t.sld + c4 * 4); } }
; __device__ __forceinline__ void tr_all(const Params& p, LAS float* sm, int b, int G, int tid) {
;     ...
;         if (nb < 1792) tr_load4(p, nb * 4, tid, v);
.LBB0_317:
	v_lshl_add_u64 v[10:11], s[50:51], 0, v[38:39]
	v_mad_i64_i32 v[12:13], s[0:1], s52, v40, 0
	v_mad_i64_i32 v[14:15], s[0:1], s52, v42, 0
	v_lshl_add_u64 v[12:13], v[12:13], 2, v[10:11]
	v_lshl_add_u64 v[14:15], v[14:15], 2, v[10:11]
	global_load_dwordx4 v[10:13], v[12:13], off nt
	s_nop 0
	global_load_dwordx4 v[14:17], v[14:15], off nt
	s_or_b32 s0, s55, 2
	s_and_b64 vcc, exec, s[4:5]
	s_mov_b64 s[52:53], -1
	s_cbranch_vccnz .LBB0_327
	s_cmpk_lt_u32 s55, 0x1800
	s_cbranch_scc1 .LBB0_320
	s_lshl_b32 s1, s0, 19
	s_and_b32 s1, s1, 0xf00000
	s_add_u32 s1, s20, s1
	s_addc_u32 s9, s21, 0
	s_lshl_b32 s6, s89, 3
	s_and_b32 s6, s6, 0x7fffffc0
	s_lshl_b64 s[28:29], s[6:7], 2
	s_add_u32 s1, s1, s28
	s_addc_u32 s6, s9, s29
	s_add_u32 s50, s1, 0xffff4000
	s_addc_u32 s51, s6, -1
	s_mov_b64 s[52:53], 0

; __device__ __forceinline__ TrJob tr_job(const Params& p, int j) {
;     ...
;     else if (j < 6144) { const int jj = j - 5120, nc = jj >> 5, kc = jj & 31;
;         t.src = (kc < 16 ? p.wpp + (size_t)(kc * 64) * D : p.wpc + (size_t)((kc - 16) * 64) * D) + nc * 64; t.sld = D; t.dst = (bf16_t*)(p.ws + WS_BP) + (size_t)(nc * 64) * LDP + kc * 64; }
;     else { const int jj = j - 6144, nc = jj >> 5, kc = jj & 31; t.src = p.wout + (size_t)(kc * 64) * D + nc * 64; t.sld = D; t.dst = (bf16_t*)(p.ws + WS_BO) + (size_t)(nc * 64) * LDP + kc * 64; }
; __device__ __forceinline__ void tr_load4(const Params& p, int j0, int tid, f32x4 (&v)[4][2]) {
; #pragma unroll
;     for (int q = 0; q < 4; ++q) { const TrJob t = tr_job(p, j0 + q);
; #pragma unroll
;         for (int i = 0; i < 2; ++i) { const int idx = tid + i * 512, kr = idx >> 4, c4 = idx & 15; v[q][i] = *(const f32x4*)(t.src + (size_t)kr * t.sld + c4 * 4); } }
; __device__ __forceinline__ void tr_all(const Params& p, LAS float* sm, int b, int G, int tid) {
;     ...
;         if (nb < 1792) tr_load4(p, nb * 4, tid, v);
.LBB0_345:
	v_lshl_add_u64 v[18:19], s[50:51], 0, v[38:39]
	v_mad_i64_i32 v[20:21], s[0:1], s52, v40, 0
	v_mad_i64_i32 v[22:23], s[0:1], s52, v42, 0
	v_lshl_add_u64 v[20:21], v[20:21], 2, v[18:19]
	v_lshl_add_u64 v[22:23], v[22:23], 2, v[18:19]
	global_load_dwordx4 v[18:21], v[20:21], off nt
	s_nop 0
	global_load_dwordx4 v[22:25], v[22:23], off nt
	s_or_b32 s0, s55, 3
	s_and_b64 vcc, exec, s[4:5]
	s_mov_b64 s[50:51], -1
	s_cbranch_vccnz .LBB0_355
	s_cmpk_lt_u32 s55, 0x1800
	s_cbranch_scc1 .LBB0_348
	s_lshl_b32 s1, s0, 19
	s_and_b32 s1, s1, 0xf80000
	s_add_u32 s1, s20, s1
	s_addc_u32 s9, s21, 0
	s_lshl_b32 s4, s89, 3
	s_and_b32 s6, s4, 0x7fffffc0
	s_lshl_b64 s[4:5], s[6:7], 2
	s_add_u32 s1, s1, s4
	s_addc_u32 s5, s9, s5
	s_add_u32 s4, s1, 0xffff4000
	s_addc_u32 s5, s5, -1
	s_mov_b64 s[50:51], 0

; __device__ __forceinline__ void tr_load4(const Params& p, int j0, int tid, f32x4 (&v)[4][2]) {
; #pragma unroll
;     for (int q = 0; q < 4; ++q) { const TrJob t = tr_job(p, j0 + q);
; #pragma unroll
;         for (int i = 0; i < 2; ++i) { const int idx = tid + i * 512, kr = idx >> 4, c4 = idx & 15; v[q][i] = *(const f32x4*)(t.src + (size_t)kr * t.sld + c4 * 4); } }
; __device__ __forceinline__ void tr_all(const Params& p, LAS float* sm, int b, int G, int tid) {
;     ...
;         if (nb < 1792) tr_load4(p, nb * 4, tid, v);
.LBB0_373:
	v_lshl_add_u64 v[26:27], s[4:5], 0, v[38:39]
	v_mad_i64_i32 v[28:29], s[0:1], s50, v40, 0
	v_mad_i64_i32 v[30:31], s[0:1], s50, v42, 0
	v_lshl_add_u64 v[28:29], v[28:29], 2, v[26:27]
	v_lshl_add_u64 v[30:31], v[30:31], 2, v[26:27]
	global_load_dwordx4 v[26:29], v[28:29], off nt
	s_nop 0
	global_load_dwordx4 v[30:33], v[30:31], off nt
